# attn_sample: the compute waves' q / gate / sink loads are requested before the cache loads (they were issued after the second barrier) and their two waits dropped
# speedup vs baseline: 1.0092x; 1.0092x over previous
.LBB0_659:
	s_add_u32 s0, s94, 0x16402800
	s_addc_u32 s1, s95, 0
	v_writelane_b32 v254, s0, 47
	s_nop 1
	v_writelane_b32 v254, s1, 48
	s_nop 0
	v_readlane_b32 s0, v254, 55
	v_readlane_b32 s1, v254, 56
	s_and_b64 vcc, exec, s[0:1]
	s_cbranch_vccnz .LBB0_684
	s_lshr_b32 s9, s2, 1
	s_and_b32 s10, s2, 1
	s_lshl_b32 s6, s9, 17
	s_lshl_b32 s7, s10, 9
	s_add_u32 s6, s6, s7
	s_add_u32 s60, s40, s6
	s_addc_u32 s61, s41, 0
	s_add_u32 s62, s42, s6
	s_addc_u32 s63, s43, 0
	s_add_u32 s7, s6, 0x44fe000
	s_add_u32 s64, s92, s7
	s_addc_u32 s65, s93, 0
	s_add_u32 s7, s6, 0x54fe000
	s_add_u32 s66, s92, s7
	s_addc_u32 s67, s93, 0
	s_add_u32 s7, s6, 0x451e000
	s_add_u32 s68, s92, s7
	s_addc_u32 s69, s93, 0
	s_add_u32 s7, s6, 0x551e000
	s_add_u32 s70, s92, s7
	s_addc_u32 s71, s93, 0
	v_lshrrev_b32_e32 v0, 4, v198
	v_and_b32_e32 v1, 15, v198
	v_lshlrev_b32_e32 v2, 10, v0
	v_lshl_add_u32 v2, v1, 4, v2
	v_add_u32_e32 v3, 0x8000, v2
	v_add_u32_e32 v4, 0x10000, v2
	v_add_u32_e32 v5, 0x18000, v2
	v_mul_u32_u24_e32 v8, 144, v0
	v_lshl_add_u32 v8, v1, 3, v8
	v_add_u32_e32 v9, 41472, v8
	v_lshrrev_b32_e32 v10, 6, v198
	v_mov_b32_e32 v12, 0
	v_mov_b32_e32 v13, 0
	v_readfirstlane_b32 s8, v10
	s_nop 1
	s_cmp_lt_u32 s8, 4
	s_cbranch_scc0 .Las_noq
	s_lshr_b32 s6, s8, 1
	s_and_b32 s7, s8, 1
	s_lshl_b32 s15, s10, 1
	s_add_u32 s15, s15, s6
	s_lshl_b32 s15, s15, 2
	s_lshl_b32 s16, s7, 1
	s_add_u32 s15, s15, s16
	s_mul_i32 s17, s6, 41472
	s_lshl_b32 s16, s9, 14
	s_add_u32 s16, s16, 0x2000000
	s_lshl_b32 s24, s15, 7
	s_add_u32 s16, s16, s24
	s_add_u32 s24, s16, 0x1a802800
	s_add_u32 s72, s94, s24
	s_addc_u32 s73, s95, 0
	s_add_u32 s24, s16, 0x1ec02800
	s_add_u32 s74, s94, s24
	s_addc_u32 s75, s95, 0
	s_add_u32 s24, s16, 0x16402800
	s_add_u32 s76, s94, s24
	s_addc_u32 s77, s95, 0
	v_readlane_b32 s78, v254, 9
	v_readlane_b32 s79, v254, 10
	s_lshl_b32 s24, s15, 2
	s_nop 1
	s_add_u32 s78, s78, s24
	s_addc_u32 s79, s79, 0
	v_and_b32_e32 v100, 15, v198
	v_bfe_u32 v101, v198, 4, 2
	v_and_b32_e32 v102, 7, v198
	v_bfe_u32 v103, v198, 3, 1
	v_lshlrev_b32_e32 v104, 11, v102
	v_lshl_add_u32 v104, v103, 7, v104
	v_lshl_add_u32 v105, v101, 3, v104
	v_lshl_add_u32 v104, v101, 4, v104
	v_lshlrev_b32_e32 v111, 2, v103
	global_load_dword v112, v111, s[78:79]
	global_load_dwordx4 v[116:119], v104, s[72:73]
	global_load_dwordx4 v[120:123], v104, s[72:73] offset:64
	global_load_dwordx2 v[124:125], v105, s[74:75]
	global_load_dwordx2 v[126:127], v105, s[74:75] offset:32
	global_load_dwordx2 v[128:129], v105, s[74:75] offset:64
	global_load_dwordx2 v[130:131], v105, s[74:75] offset:96
.Las_noq:
	global_load_dwordx4 v[16:19], v2, s[60:61]
	global_load_dwordx4 v[20:23], v3, s[60:61]
	global_load_dwordx4 v[24:27], v4, s[60:61]
	global_load_dwordx4 v[28:31], v5, s[60:61]
	global_load_dwordx4 v[32:35], v2, s[62:63]
	global_load_dwordx4 v[36:39], v3, s[62:63]
	global_load_dwordx4 v[40:43], v4, s[62:63]
	global_load_dwordx4 v[44:47], v5, s[62:63]
	global_load_dwordx4 v[48:51], v2, s[60:61] offset:256
	global_load_dwordx4 v[52:55], v3, s[60:61] offset:256
	global_load_dwordx4 v[56:59], v4, s[60:61] offset:256
	global_load_dwordx4 v[60:63], v5, s[60:61] offset:256
	global_load_dwordx4 v[64:67], v2, s[62:63] offset:256
	global_load_dwordx4 v[68:71], v3, s[62:63] offset:256
	global_load_dwordx4 v[72:75], v4, s[62:63] offset:256
	global_load_dwordx4 v[76:79], v5, s[62:63] offset:256
	s_cmp_lt_u32 s8, 2
	s_cbranch_scc0 .Las_noextra_ld
	global_load_dwordx4 v[80:83], v2, s[68:69]
	global_load_dwordx4 v[84:87], v2, s[70:71]
	global_load_dwordx4 v[88:91], v2, s[68:69] offset:256
	global_load_dwordx4 v[92:95], v2, s[70:71] offset:256

.Las_noextra_st:
	s_waitcnt lgkmcnt(0)
	s_barrier
	s_cmp_lt_u32 s8, 4
	s_cbranch_scc0 .Las_done
	v_mul_u32_u24_e32 v106, 144, v100
	v_lshl_add_u32 v106, v101, 4, v106
	v_add_u32_e32 v106, s17, v106
	v_lshrrev_b32_e32 v107, 2, v100
	v_lshl_add_u32 v107, v101, 2, v107
	v_mul_u32_u24_e32 v107, 144, v107
	v_and_b32_e32 v113, 3, v100
	v_lshl_add_u32 v107, v113, 3, v107
	v_add_u32_e32 v107, s17, v107
	v_add_u32_e32 v107, 20736, v107
	v_lshlrev_b32_e32 v113, 2, v101
	v_sub_u32_e32 v108, v102, v113
	v_and_b32_e32 v113, 63, v198
	v_xor_b32_e32 v109, 16, v113
	v_lshlrev_b32_e32 v109, 2, v109
	v_xor_b32_e32 v110, 32, v113
	v_lshlrev_b32_e32 v110, 2, v110
	ds_read_b128 v[52:55], v106 offset:0
	ds_read_b128 v[56:59], v106 offset:64
	ds_read_b128 v[60:63], v106 offset:2304
	ds_read_b128 v[64:67], v106 offset:2368
	s_waitcnt lgkmcnt(3)
	v_mfma_f32_16x16x32_bf16 v[16:19], v[52:55], v[116:119], 0
	ds_read_b128 v[52:55], v106 offset:4608
	s_waitcnt lgkmcnt(3)
	v_mfma_f32_16x16x32_bf16 v[16:19], v[56:59], v[120:123], v[16:19]
	ds_read_b128 v[56:59], v106 offset:4672
	s_waitcnt lgkmcnt(3)
	v_mfma_f32_16x16x32_bf16 v[20:23], v[60:63], v[116:119], 0
	ds_read_b128 v[60:63], v106 offset:6912
	s_waitcnt lgkmcnt(3)
	v_mfma_f32_16x16x32_bf16 v[20:23], v[64:67], v[120:123], v[20:23]
	ds_read_b128 v[64:67], v106 offset:6976
	s_waitcnt lgkmcnt(3)
	v_mfma_f32_16x16x32_bf16 v[24:27], v[52:55], v[116:119], 0
	ds_read_b128 v[52:55], v106 offset:9216
	s_waitcnt lgkmcnt(3)
	v_mfma_f32_16x16x32_bf16 v[24:27], v[56:59], v[120:123], v[24:27]
	ds_read_b128 v[56:59], v106 offset:9280
	s_waitcnt lgkmcnt(3)
	v_mfma_f32_16x16x32_bf16 v[28:31], v[60:63], v[116:119], 0
	ds_read_b128 v[60:63], v106 offset:11520
	s_waitcnt lgkmcnt(3)
	v_mfma_f32_16x16x32_bf16 v[28:31], v[64:67], v[120:123], v[28:31]
	ds_read_b128 v[64:67], v106 offset:11584
	s_waitcnt lgkmcnt(3)
	v_mfma_f32_16x16x32_bf16 v[32:35], v[52:55], v[116:119], 0
	ds_read_b128 v[52:55], v106 offset:13824
	s_waitcnt lgkmcnt(3)
	v_mfma_f32_16x16x32_bf16 v[32:35], v[56:59], v[120:123], v[32:35]
	ds_read_b128 v[56:59], v106 offset:13888
	s_waitcnt lgkmcnt(3)
	v_mfma_f32_16x16x32_bf16 v[36:39], v[60:63], v[116:119], 0
	ds_read_b128 v[60:63], v106 offset:16128
	s_waitcnt lgkmcnt(3)
	v_mfma_f32_16x16x32_bf16 v[36:39], v[64:67], v[120:123], v[36:39]
	ds_read_b128 v[64:67], v106 offset:16192
	s_waitcnt lgkmcnt(3)
	v_mfma_f32_16x16x32_bf16 v[40:43], v[52:55], v[116:119], 0
	ds_read_b128 v[52:55], v106 offset:18432
	s_waitcnt lgkmcnt(3)
	v_mfma_f32_16x16x32_bf16 v[40:43], v[56:59], v[120:123], v[40:43]
	ds_read_b128 v[56:59], v106 offset:18496
	s_waitcnt lgkmcnt(3)
	v_mfma_f32_16x16x32_bf16 v[44:47], v[60:63], v[116:119], 0
	s_waitcnt lgkmcnt(2)
	v_mfma_f32_16x16x32_bf16 v[44:47], v[64:67], v[120:123], v[44:47]
	s_waitcnt lgkmcnt(1)
	v_mfma_f32_16x16x32_bf16 v[48:51], v[52:55], v[116:119], 0
	s_waitcnt lgkmcnt(0)
	v_mfma_f32_16x16x32_bf16 v[48:51], v[56:59], v[120:123], v[48:51]
	s_nop 7
	v_mov_b32_e32 v114, 0xf149f2ca
	v_cmp_gt_i32_e32 vcc, 0, v108
	s_nop 1
	v_cndmask_b32_e32 v16, v114, v16, vcc
	v_cmp_gt_i32_e32 vcc, 1, v108
	s_nop 1
	v_cndmask_b32_e32 v17, v114, v17, vcc
	v_cmp_gt_i32_e32 vcc, 2, v108
	s_nop 1
	v_cndmask_b32_e32 v18, v114, v18, vcc
	v_cmp_gt_i32_e32 vcc, 3, v108
	s_nop 1
	v_cndmask_b32_e32 v19, v114, v19, vcc
	v_cmp_le_i32_e32 vcc, 0, v108
	s_nop 1
	v_cndmask_b32_e32 v48, v114, v48, vcc
	v_cmp_le_i32_e32 vcc, 1, v108
	s_nop 1
	v_cndmask_b32_e32 v49, v114, v49, vcc
	v_cmp_le_i32_e32 vcc, 2, v108
	s_nop 1
	v_cndmask_b32_e32 v50, v114, v50, vcc
	v_cmp_le_i32_e32 vcc, 3, v108
	s_nop 1
	v_cndmask_b32_e32 v51, v114, v51, vcc
	v_max3_f32 v68, v112, v16, v17
	v_max3_f32 v68, v68, v18, v19
	v_max3_f32 v68, v68, v20, v21
	v_max3_f32 v68, v68, v22, v23
	v_max3_f32 v68, v68, v24, v25
	v_max3_f32 v68, v68, v26, v27
	v_max3_f32 v68, v68, v28, v29
	v_max3_f32 v68, v68, v30, v31
	v_max3_f32 v68, v68, v32, v33
	v_max3_f32 v68, v68, v34, v35
	v_max3_f32 v68, v68, v36, v37
	v_max3_f32 v68, v68, v38, v39
	v_max3_f32 v68, v68, v40, v41
	v_max3_f32 v68, v68, v42, v43
	v_max3_f32 v68, v68, v44, v45
	v_max3_f32 v68, v68, v46, v47
	v_max3_f32 v68, v68, v48, v49
	v_max3_f32 v68, v68, v50, v51
	ds_bpermute_b32 v69, v109, v68
	s_waitcnt lgkmcnt(0)
	v_max_f32_e32 v68, v68, v69
	ds_bpermute_b32 v69, v110, v68
	s_waitcnt lgkmcnt(0)
	v_max_f32_e32 v68, v68, v69
	v_sub_f32_e32 v16, v16, v68
	v_mul_f32_e32 v16, 0x3fb8aa3b, v16
	v_exp_f32_e32 v16, v16
	v_sub_f32_e32 v17, v17, v68
	v_mul_f32_e32 v17, 0x3fb8aa3b, v17
	v_exp_f32_e32 v17, v17
	v_sub_f32_e32 v18, v18, v68
	v_mul_f32_e32 v18, 0x3fb8aa3b, v18
	v_exp_f32_e32 v18, v18
	v_sub_f32_e32 v19, v19, v68
	v_mul_f32_e32 v19, 0x3fb8aa3b, v19
	v_exp_f32_e32 v19, v19
	v_sub_f32_e32 v20, v20, v68
	v_mul_f32_e32 v20, 0x3fb8aa3b, v20
	v_exp_f32_e32 v20, v20
	v_sub_f32_e32 v21, v21, v68
	v_mul_f32_e32 v21, 0x3fb8aa3b, v21
	v_exp_f32_e32 v21, v21
	v_sub_f32_e32 v22, v22, v68
	v_mul_f32_e32 v22, 0x3fb8aa3b, v22
	v_exp_f32_e32 v22, v22
	v_sub_f32_e32 v23, v23, v68
	v_mul_f32_e32 v23, 0x3fb8aa3b, v23
	v_exp_f32_e32 v23, v23
	v_sub_f32_e32 v24, v24, v68
	v_mul_f32_e32 v24, 0x3fb8aa3b, v24
	v_exp_f32_e32 v24, v24
	v_sub_f32_e32 v25, v25, v68
	v_mul_f32_e32 v25, 0x3fb8aa3b, v25
	v_exp_f32_e32 v25, v25
	v_sub_f32_e32 v26, v26, v68
	v_mul_f32_e32 v26, 0x3fb8aa3b, v26
	v_exp_f32_e32 v26, v26
	v_sub_f32_e32 v27, v27, v68
	v_mul_f32_e32 v27, 0x3fb8aa3b, v27
	v_exp_f32_e32 v27, v27
	v_sub_f32_e32 v28, v28, v68
	v_mul_f32_e32 v28, 0x3fb8aa3b, v28
	v_exp_f32_e32 v28, v28
	v_sub_f32_e32 v29, v29, v68
	v_mul_f32_e32 v29, 0x3fb8aa3b, v29
	v_exp_f32_e32 v29, v29
	v_sub_f32_e32 v30, v30, v68
	v_mul_f32_e32 v30, 0x3fb8aa3b, v30
	v_exp_f32_e32 v30, v30
	v_sub_f32_e32 v31, v31, v68
	v_mul_f32_e32 v31, 0x3fb8aa3b, v31
	v_exp_f32_e32 v31, v31
	v_sub_f32_e32 v32, v32, v68
	v_mul_f32_e32 v32, 0x3fb8aa3b, v32
	v_exp_f32_e32 v32, v32
	v_sub_f32_e32 v33, v33, v68
	v_mul_f32_e32 v33, 0x3fb8aa3b, v33
	v_exp_f32_e32 v33, v33
	v_sub_f32_e32 v34, v34, v68
	v_mul_f32_e32 v34, 0x3fb8aa3b, v34
	v_exp_f32_e32 v34, v34
	v_sub_f32_e32 v35, v35, v68
	v_mul_f32_e32 v35, 0x3fb8aa3b, v35
	v_exp_f32_e32 v35, v35
	v_sub_f32_e32 v36, v36, v68
	v_mul_f32_e32 v36, 0x3fb8aa3b, v36
	v_exp_f32_e32 v36, v36
	v_sub_f32_e32 v37, v37, v68
	v_mul_f32_e32 v37, 0x3fb8aa3b, v37
	v_exp_f32_e32 v37, v37
	v_sub_f32_e32 v38, v38, v68
	v_mul_f32_e32 v38, 0x3fb8aa3b, v38
	v_exp_f32_e32 v38, v38
	v_sub_f32_e32 v39, v39, v68
	v_mul_f32_e32 v39, 0x3fb8aa3b, v39
	v_exp_f32_e32 v39, v39
	v_sub_f32_e32 v40, v40, v68
	v_mul_f32_e32 v40, 0x3fb8aa3b, v40
	v_exp_f32_e32 v40, v40
	v_sub_f32_e32 v41, v41, v68
	v_mul_f32_e32 v41, 0x3fb8aa3b, v41
	v_exp_f32_e32 v41, v41
	v_sub_f32_e32 v42, v42, v68
	v_mul_f32_e32 v42, 0x3fb8aa3b, v42
	v_exp_f32_e32 v42, v42
	v_sub_f32_e32 v43, v43, v68
	v_mul_f32_e32 v43, 0x3fb8aa3b, v43
	v_exp_f32_e32 v43, v43
	v_sub_f32_e32 v44, v44, v68
	v_mul_f32_e32 v44, 0x3fb8aa3b, v44
	v_exp_f32_e32 v44, v44
	v_sub_f32_e32 v45, v45, v68
	v_mul_f32_e32 v45, 0x3fb8aa3b, v45
	v_exp_f32_e32 v45, v45
	v_sub_f32_e32 v46, v46, v68
	v_mul_f32_e32 v46, 0x3fb8aa3b, v46
	v_exp_f32_e32 v46, v46
	v_sub_f32_e32 v47, v47, v68
	v_mul_f32_e32 v47, 0x3fb8aa3b, v47
	v_exp_f32_e32 v47, v47
	v_sub_f32_e32 v48, v48, v68
	v_mul_f32_e32 v48, 0x3fb8aa3b, v48
	v_exp_f32_e32 v48, v48
	v_sub_f32_e32 v49, v49, v68
	v_mul_f32_e32 v49, 0x3fb8aa3b, v49
	v_exp_f32_e32 v49, v49
	v_sub_f32_e32 v50, v50, v68
	v_mul_f32_e32 v50, 0x3fb8aa3b, v50
	v_exp_f32_e32 v50, v50
	v_sub_f32_e32 v51, v51, v68
	v_mul_f32_e32 v51, 0x3fb8aa3b, v51
	v_exp_f32_e32 v51, v51
	s_nop 0
	v_add_f32_e32 v71, v16, v17
	v_add_f32_e32 v71, v71, v18
	v_add_f32_e32 v71, v71, v19
	v_add_f32_e32 v71, v71, v20
	v_add_f32_e32 v71, v71, v21
	v_add_f32_e32 v71, v71, v22
	v_add_f32_e32 v71, v71, v23
	v_add_f32_e32 v71, v71, v24
	v_add_f32_e32 v71, v71, v25
	v_add_f32_e32 v71, v71, v26
	v_add_f32_e32 v71, v71, v27
	v_add_f32_e32 v71, v71, v28
	v_add_f32_e32 v71, v71, v29
	v_add_f32_e32 v71, v71, v30
	v_add_f32_e32 v71, v71, v31
	v_add_f32_e32 v71, v71, v32
	v_add_f32_e32 v71, v71, v33
	v_add_f32_e32 v71, v71, v34
	v_add_f32_e32 v71, v71, v35
	v_add_f32_e32 v71, v71, v36
	v_add_f32_e32 v71, v71, v37
	v_add_f32_e32 v71, v71, v38
	v_add_f32_e32 v71, v71, v39
	v_add_f32_e32 v71, v71, v40
	v_add_f32_e32 v71, v71, v41
	v_add_f32_e32 v71, v71, v42
	v_add_f32_e32 v71, v71, v43
	v_add_f32_e32 v71, v71, v44
	v_add_f32_e32 v71, v71, v45
	v_add_f32_e32 v71, v71, v46
	v_add_f32_e32 v71, v71, v47
	v_add_f32_e32 v71, v71, v48
	v_add_f32_e32 v71, v71, v49
	v_add_f32_e32 v71, v71, v50
	v_add_f32_e32 v71, v71, v51
	ds_bpermute_b32 v69, v109, v71
	s_waitcnt lgkmcnt(0)
	v_add_f32_e32 v71, v71, v69
	ds_bpermute_b32 v69, v110, v71
	s_waitcnt lgkmcnt(0)
	v_add_f32_e32 v71, v71, v69
	v_sub_f32_e32 v69, v112, v68
	v_mul_f32_e32 v69, 0x3fb8aa3b, v69
	v_exp_f32_e32 v69, v69
	s_nop 0
	v_add_f32_e32 v71, v71, v69
	v_rcp_f32_e32 v72, v71
	s_nop 0
	v_fma_f32 v70, -v71, v72, 1.0
	v_fma_f32 v72, v72, v70, v72
	v_mov_b32_e32 v73, v72
	v_cvt_pk_bf16_f32 v76, v16, v17
	v_cvt_pk_bf16_f32 v77, v18, v19
	v_cvt_pk_bf16_f32 v78, v20, v21
	v_cvt_pk_bf16_f32 v79, v22, v23
	v_cvt_pk_bf16_f32 v80, v24, v25
	v_cvt_pk_bf16_f32 v81, v26, v27
	v_cvt_pk_bf16_f32 v82, v28, v29
	v_cvt_pk_bf16_f32 v83, v30, v31
	v_cvt_pk_bf16_f32 v84, v32, v33
	v_cvt_pk_bf16_f32 v85, v34, v35
	v_cvt_pk_bf16_f32 v86, v36, v37
	v_cvt_pk_bf16_f32 v87, v38, v39
	v_cvt_pk_bf16_f32 v88, v40, v41
	v_cvt_pk_bf16_f32 v89, v42, v43
	v_cvt_pk_bf16_f32 v90, v44, v45
	v_cvt_pk_bf16_f32 v91, v46, v47
	v_cvt_pk_bf16_f32 v92, v48, v49
	v_cvt_pk_bf16_f32 v93, v50, v51
	v_mov_b32_e32 v94, 0
	v_mov_b32_e32 v95, 0
	ds_read_b64_tr_b16 v[16:17], v107 offset:0
	ds_read_b64_tr_b16 v[18:19], v107 offset:2304
	ds_read_b64_tr_b16 v[20:21], v107 offset:32
	ds_read_b64_tr_b16 v[22:23], v107 offset:2336
	ds_read_b64_tr_b16 v[24:25], v107 offset:64
	ds_read_b64_tr_b16 v[26:27], v107 offset:2368
	ds_read_b64_tr_b16 v[28:29], v107 offset:96
	ds_read_b64_tr_b16 v[30:31], v107 offset:2400
	s_waitcnt lgkmcnt(6)
	v_mfma_f32_16x16x32_bf16 v[132:135], v[16:19], v[76:79], 0
	ds_read_b64_tr_b16 v[16:17], v107 offset:4608
	ds_read_b64_tr_b16 v[18:19], v107 offset:6912
	s_waitcnt lgkmcnt(6)
	v_mfma_f32_16x16x32_bf16 v[136:139], v[20:23], v[76:79], 0
	ds_read_b64_tr_b16 v[20:21], v107 offset:4640
	ds_read_b64_tr_b16 v[22:23], v107 offset:6944
	s_waitcnt lgkmcnt(6)
	v_mfma_f32_16x16x32_bf16 v[140:143], v[24:27], v[76:79], 0
	ds_read_b64_tr_b16 v[24:25], v107 offset:4672
	ds_read_b64_tr_b16 v[26:27], v107 offset:6976
	s_waitcnt lgkmcnt(6)
	v_mfma_f32_16x16x32_bf16 v[144:147], v[28:31], v[76:79], 0
	ds_read_b64_tr_b16 v[28:29], v107 offset:4704
	ds_read_b64_tr_b16 v[30:31], v107 offset:7008
	s_waitcnt lgkmcnt(6)
	v_mfma_f32_16x16x32_bf16 v[132:135], v[16:19], v[80:83], v[132:135]
	ds_read_b64_tr_b16 v[16:17], v107 offset:9216
	ds_read_b64_tr_b16 v[18:19], v107 offset:11520
	s_waitcnt lgkmcnt(6)
	v_mfma_f32_16x16x32_bf16 v[136:139], v[20:23], v[80:83], v[136:139]
	ds_read_b64_tr_b16 v[20:21], v107 offset:9248
	ds_read_b64_tr_b16 v[22:23], v107 offset:11552
	s_waitcnt lgkmcnt(6)
	v_mfma_f32_16x16x32_bf16 v[140:143], v[24:27], v[80:83], v[140:143]
	ds_read_b64_tr_b16 v[24:25], v107 offset:9280
	ds_read_b64_tr_b16 v[26:27], v107 offset:11584
	s_waitcnt lgkmcnt(6)
	v_mfma_f32_16x16x32_bf16 v[144:147], v[28:31], v[80:83], v[144:147]
	ds_read_b64_tr_b16 v[28:29], v107 offset:9312
	ds_read_b64_tr_b16 v[30:31], v107 offset:11616
	s_waitcnt lgkmcnt(6)
	v_mfma_f32_16x16x32_bf16 v[132:135], v[16:19], v[84:87], v[132:135]
	ds_read_b64_tr_b16 v[16:17], v107 offset:13824
	ds_read_b64_tr_b16 v[18:19], v107 offset:16128
	s_waitcnt lgkmcnt(6)
	v_mfma_f32_16x16x32_bf16 v[136:139], v[20:23], v[84:87], v[136:139]
	ds_read_b64_tr_b16 v[20:21], v107 offset:13856
	ds_read_b64_tr_b16 v[22:23], v107 offset:16160
	s_waitcnt lgkmcnt(6)
	v_mfma_f32_16x16x32_bf16 v[140:143], v[24:27], v[84:87], v[140:143]
	ds_read_b64_tr_b16 v[24:25], v107 offset:13888
	ds_read_b64_tr_b16 v[26:27], v107 offset:16192
	s_waitcnt lgkmcnt(6)
	v_mfma_f32_16x16x32_bf16 v[144:147], v[28:31], v[84:87], v[144:147]
	ds_read_b64_tr_b16 v[28:29], v107 offset:13920
	ds_read_b64_tr_b16 v[30:31], v107 offset:16224
	s_waitcnt lgkmcnt(6)
	v_mfma_f32_16x16x32_bf16 v[132:135], v[16:19], v[88:91], v[132:135]
	ds_read_b64_tr_b16 v[16:17], v107 offset:18432
	ds_read_b64_tr_b16 v[18:19], v107 offset:18432
	s_waitcnt lgkmcnt(6)
	v_mfma_f32_16x16x32_bf16 v[136:139], v[20:23], v[88:91], v[136:139]
	ds_read_b64_tr_b16 v[20:21], v107 offset:18464
	ds_read_b64_tr_b16 v[22:23], v107 offset:18464
	s_waitcnt lgkmcnt(6)
	v_mfma_f32_16x16x32_bf16 v[140:143], v[24:27], v[88:91], v[140:143]
	ds_read_b64_tr_b16 v[24:25], v107 offset:18496
	ds_read_b64_tr_b16 v[26:27], v107 offset:18496
	s_waitcnt lgkmcnt(6)
	v_mfma_f32_16x16x32_bf16 v[144:147], v[28:31], v[88:91], v[144:147]
	ds_read_b64_tr_b16 v[28:29], v107 offset:18528
	ds_read_b64_tr_b16 v[30:31], v107 offset:18528
	s_waitcnt lgkmcnt(6)
	v_mfma_f32_16x16x32_bf16 v[132:135], v[16:19], v[92:95], v[132:135]
	s_waitcnt lgkmcnt(4)
	v_mfma_f32_16x16x32_bf16 v[136:139], v[20:23], v[92:95], v[136:139]
	s_waitcnt lgkmcnt(2)
	v_mfma_f32_16x16x32_bf16 v[140:143], v[24:27], v[92:95], v[140:143]
	s_waitcnt lgkmcnt(0)
	v_mfma_f32_16x16x32_bf16 v[144:147], v[28:31], v[92:95], v[144:147]
	s_nop 7
	v_lshlrev_b32_e32 v52, 16, v124
	v_and_b32_e32 v53, 0xffff0000, v124
	v_lshlrev_b32_e32 v54, 16, v125
	v_and_b32_e32 v55, 0xffff0000, v125
	v_pk_mul_f32 v[132:133], v[132:133], v[72:73]
	v_pk_mul_f32 v[134:135], v[134:135], v[72:73]
	v_pk_mul_f32 v[132:133], v[132:133], v[52:53]
	v_pk_mul_f32 v[134:135], v[134:135], v[54:55]
	v_cvt_pk_bf16_f32 v56, v132, v133
	v_cvt_pk_bf16_f32 v57, v134, v135
	global_store_dwordx2 v105, v[56:57], s[76:77]
	v_lshlrev_b32_e32 v52, 16, v126
	v_and_b32_e32 v53, 0xffff0000, v126
	v_lshlrev_b32_e32 v54, 16, v127
	v_and_b32_e32 v55, 0xffff0000, v127
	v_pk_mul_f32 v[136:137], v[136:137], v[72:73]
	v_pk_mul_f32 v[138:139], v[138:139], v[72:73]
	v_pk_mul_f32 v[136:137], v[136:137], v[52:53]
	v_pk_mul_f32 v[138:139], v[138:139], v[54:55]
	v_cvt_pk_bf16_f32 v56, v136, v137
	v_cvt_pk_bf16_f32 v57, v138, v139
	global_store_dwordx2 v105, v[56:57], s[76:77] offset:32
	v_lshlrev_b32_e32 v52, 16, v128
	v_and_b32_e32 v53, 0xffff0000, v128
	v_lshlrev_b32_e32 v54, 16, v129
	v_and_b32_e32 v55, 0xffff0000, v129
	v_pk_mul_f32 v[140:141], v[140:141], v[72:73]
	v_pk_mul_f32 v[142:143], v[142:143], v[72:73]
	v_pk_mul_f32 v[140:141], v[140:141], v[52:53]
	v_pk_mul_f32 v[142:143], v[142:143], v[54:55]
	v_cvt_pk_bf16_f32 v56, v140, v141
	v_cvt_pk_bf16_f32 v57, v142, v143
	global_store_dwordx2 v105, v[56:57], s[76:77] offset:64
	v_lshlrev_b32_e32 v52, 16, v130
	v_and_b32_e32 v53, 0xffff0000, v130
	v_lshlrev_b32_e32 v54, 16, v131
	v_and_b32_e32 v55, 0xffff0000, v131
	v_pk_mul_f32 v[144:145], v[144:145], v[72:73]
	v_pk_mul_f32 v[146:147], v[146:147], v[72:73]
	v_pk_mul_f32 v[144:145], v[144:145], v[52:53]
	v_pk_mul_f32 v[146:147], v[146:147], v[54:55]
	v_cvt_pk_bf16_f32 v56, v144, v145
	v_cvt_pk_bf16_f32 v57, v146, v147
	global_store_dwordx2 v105, v[56:57], s[76:77] offset:96
